# scanner: separate warm-up loop, one taken branch per interval placed before the barrier, next-chunk LDS addresses computed in the wait-state slots of the last two tokens
# baseline (speedup 1.0000x reference)
; #define LAS __attribute__((address_space(3)))
; #define SCAN_BAR() do { asm volatile("s_waitcnt lgkmcnt(0)" ::: "memory"); __builtin_amdgcn_s_barrier(); asm volatile("" ::: "memory"); } while (0)
; __device__ __forceinline__ void phase_scan(const Args& a, int l, LAS unsigned char* lds) {
;     ...
;             for (int it = -6; it < NCH; ++it) {
;                 if (it >= 0) {
;                     const LAS float* tb = buf + (it % NB) * TC * TOKF;
;                     LAS float* yb = ybuf + (it & 1) * TC * 16;
;                     f32x4 w = *(const LAS f32x4*)(tb + 4 * j), kk = *(const LAS f32x4*)(tb + 64 + 4 * j), bv = *(const LAS f32x4*)(tb + 128 + 4 * j);
;                     f32x4 kv = *(const LAS f32x4*)(tb + 192 + 4 * j), wr = *(const LAS f32x4*)(tb + 256 + 4 * j);
;                     float vv = tb[320 + rowl];
;     ...
;                 SCAN_BAR();
.LBB0_167:
	s_add_i32 s0, s0, 1
	s_addk_i32 s1, 0x100
	s_waitcnt lgkmcnt(0)
	s_barrier
	s_cmp_lt_i32 s0, 0
	s_cbranch_scc1 .LBB0_167
	s_and_b32 s38, s0, 0xff
	s_mulk_i32 s38, 0xcd
	s_lshr_b32 s38, s38, 10
	s_mul_i32 s38, s38, 5
	s_sub_i32 s38, s0, s38
	s_and_b32 s38, s38, 0xff
	s_mulk_i32 s38, 0x5500
	v_lshl_add_u32 v50, v192, 2, s38
	v_lshl_add_u32 v51, v103, 2, s38
	s_and_b32 s38, s1, 0x100
	s_branch .LBB0_168

; #define LAS __attribute__((address_space(3)))
; __device__ __forceinline__ float allred16(float x) { x += dpp_f<0xB1>(x); x += dpp_f<0x4E>(x); x += dpp_f<0x141>(x); x += dpp_f<0x140>(x); return x; }
; __device__ __forceinline__ void phase_scan(const Args& a, int l, LAS unsigned char* lds) {
;     ...
;                     f32x4 w = *(const LAS f32x4*)(tb + 4 * j), kk = *(const LAS f32x4*)(tb + 64 + 4 * j), bv = *(const LAS f32x4*)(tb + 128 + 4 * j);
;                     f32x4 kv = *(const LAS f32x4*)(tb + 192 + 4 * j), wr = *(const LAS f32x4*)(tb + 256 + 4 * j);
;                     float vv = tb[320 + rowl];
;                     float yv = 0.f;
; #pragma unroll
;                     for (int t = 0; t < TC; ++t) {
;                         f32x4 nw = w, nkk = kk, nbv = bv, nkv = kv, nwr = wr; float nvv = vv;
;                         if (t + 1 < TC) { const LAS float* p = tb + (t + 1) * TOKF;
;                             nw = *(const LAS f32x4*)(p + 4 * j); nkk = *(const LAS f32x4*)(p + 64 + 4 * j); nbv = *(const LAS f32x4*)(p + 128 + 4 * j);
;                             nkv = *(const LAS f32x4*)(p + 192 + 4 * j); nwr = *(const LAS f32x4*)(p + 256 + 4 * j); nvv = p[320 + rowl]; }
;                         f32x2 ta = Sl * kk.lo; ta = Sh * kk.hi + ta;
;                         float pa = ta.x + ta.y;
;                         const f32x2 tl = Sl * w.lo + kv.lo * vv, th = Sh * w.hi + kv.hi * vv;
;                         pa = allred16(pa);
;                         Sl = bv.lo * pa + tl;
;                         Sh = bv.hi * pa + th;
;                         f32x2 ty = Sl * wr.lo; ty = Sh * wr.hi + ty;
;                         float y = ty.x + ty.y;
;                         y = allred16(y);
;                         yv = (j == t) ? y : yv;
;                         w = nw; kk = nkk; bv = nbv; kv = nkv; wr = nwr; vv = nvv;
;                     }
.LBB0_168:
	ds_read_b128 v[10:13], v50 offset:256
	ds_read_b128 v[6:9], v50 offset:0
	ds_read_b128 v[18:21], v50 offset:768
	ds_read_b32 v26, v51 offset:1280
	ds_read_b128 v[14:17], v50 offset:512
	ds_read_b128 v[22:25], v50 offset:1024
	ds_read_b128 v[32:35], v50 offset:1616
	ds_read_b128 v[28:31], v50 offset:1360
	ds_read_b128 v[40:43], v50 offset:2128
	ds_read_b32 v48, v51 offset:2640
	ds_read_b128 v[36:39], v50 offset:1872
	ds_read_b128 v[44:47], v50 offset:2384
	s_waitcnt lgkmcnt(6)
	v_pk_mul_f32 v[76:77], v[2:3], v[10:11]
	ds_read_b128 v[58:61], v50 offset:2976
	v_pk_fma_f32 v[76:77], v[4:5], v[12:13], v[76:77]
	v_pk_mul_f32 v[80:81], v[18:19], v[26:27] op_sel_hi:[1,0]
	v_add_f32_e32 v78, v76, v77
	v_pk_mul_f32 v[82:83], v[20:21], v[26:27] op_sel_hi:[1,0]
	s_nop 0
	v_add_f32_dpp v78, v78, v78 quad_perm:[1,0,3,2] row_mask:0xf bank_mask:0xf bound_ctrl:1
	v_pk_fma_f32 v[80:81], v[2:3], v[6:7], v[80:81]
	s_nop 0
	v_add_f32_dpp v78, v78, v78 quad_perm:[2,3,0,1] row_mask:0xf bank_mask:0xf bound_ctrl:1
	v_pk_fma_f32 v[82:83], v[4:5], v[8:9], v[82:83]
	s_nop 0
	v_add_f32_dpp v78, v78, v78 row_half_mirror row_mask:0xf bank_mask:0xf bound_ctrl:1
	ds_read_b128 v[54:57], v50 offset:2720
	ds_read_b128 v[66:69], v50 offset:3488
	v_add_f32_dpp v78, v78, v78 row_mirror row_mask:0xf bank_mask:0xf bound_ctrl:1
	v_pk_fma_f32 v[2:3], v[14:15], v[78:79], v[80:81] op_sel_hi:[1,0,1]
	v_pk_fma_f32 v[4:5], v[16:17], v[78:79], v[82:83] op_sel_hi:[1,0,1]
	ds_read_b32 v74, v51 offset:4000
	ds_read_b128 v[62:65], v50 offset:3232
	ds_read_b128 v[70:73], v50 offset:3744
	s_waitcnt lgkmcnt(6)
	v_pk_mul_f32 v[76:77], v[2:3], v[32:33]
	ds_read_b128 v[108:111], v50 offset:4336
	v_pk_fma_f32 v[76:77], v[4:5], v[34:35], v[76:77]
	v_pk_mul_f32 v[80:81], v[40:41], v[48:49] op_sel_hi:[1,0]
	v_add_f32_e32 v78, v76, v77
	v_pk_mul_f32 v[82:83], v[42:43], v[48:49] op_sel_hi:[1,0]
	v_pk_mul_f32 v[84:85], v[22:23], v[2:3]
	v_add_f32_dpp v78, v78, v78 quad_perm:[1,0,3,2] row_mask:0xf bank_mask:0xf bound_ctrl:1
	v_pk_fma_f32 v[84:85], v[24:25], v[4:5], v[84:85]
	v_pk_fma_f32 v[80:81], v[2:3], v[28:29], v[80:81]
	v_add_f32_dpp v78, v78, v78 quad_perm:[2,3,0,1] row_mask:0xf bank_mask:0xf bound_ctrl:1
	v_add_f32_e32 v86, v84, v85
	v_pk_fma_f32 v[82:83], v[4:5], v[30:31], v[82:83]
	v_add_f32_dpp v78, v78, v78 row_half_mirror row_mask:0xf bank_mask:0xf bound_ctrl:1
	ds_read_b128 v[104:107], v50 offset:4080
	ds_read_b128 v[116:119], v50 offset:4848
	v_add_f32_dpp v78, v78, v78 row_mirror row_mask:0xf bank_mask:0xf bound_ctrl:1
	v_pk_fma_f32 v[2:3], v[36:37], v[78:79], v[80:81] op_sel_hi:[1,0,1]
	v_pk_fma_f32 v[4:5], v[38:39], v[78:79], v[82:83] op_sel_hi:[1,0,1]
	ds_read_b32 v124, v51 offset:5360
	ds_read_b128 v[112:115], v50 offset:4592
	ds_read_b128 v[120:123], v50 offset:5104
	s_waitcnt lgkmcnt(6)
	v_pk_mul_f32 v[76:77], v[2:3], v[58:59]
	ds_read_b128 v[10:13], v50 offset:5696
	v_pk_fma_f32 v[76:77], v[4:5], v[60:61], v[76:77]
	v_pk_mul_f32 v[80:81], v[66:67], v[74:75] op_sel_hi:[1,0]
	v_add_f32_e32 v78, v76, v77
	v_pk_mul_f32 v[82:83], v[68:69], v[74:75] op_sel_hi:[1,0]
	v_pk_mul_f32 v[84:85], v[44:45], v[2:3]
	v_add_f32_dpp v78, v78, v78 quad_perm:[1,0,3,2] row_mask:0xf bank_mask:0xf bound_ctrl:1
	v_pk_fma_f32 v[84:85], v[46:47], v[4:5], v[84:85]
	v_pk_fma_f32 v[80:81], v[2:3], v[54:55], v[80:81]
	v_add_f32_dpp v78, v78, v78 quad_perm:[2,3,0,1] row_mask:0xf bank_mask:0xf bound_ctrl:1
	v_add_f32_e32 v87, v84, v85
	v_pk_fma_f32 v[82:83], v[4:5], v[56:57], v[82:83]
	v_add_f32_dpp v78, v78, v78 row_half_mirror row_mask:0xf bank_mask:0xf bound_ctrl:1
	ds_read_b128 v[6:9], v50 offset:5440
	ds_read_b128 v[18:21], v50 offset:6208
	v_add_f32_dpp v78, v78, v78 row_mirror row_mask:0xf bank_mask:0xf bound_ctrl:1
	v_pk_fma_f32 v[2:3], v[62:63], v[78:79], v[80:81] op_sel_hi:[1,0,1]
	v_pk_fma_f32 v[4:5], v[64:65], v[78:79], v[82:83] op_sel_hi:[1,0,1]
	ds_read_b32 v26, v51 offset:6720
	ds_read_b128 v[14:17], v50 offset:5952
	ds_read_b128 v[22:25], v50 offset:6464
	s_waitcnt lgkmcnt(6)
	v_pk_mul_f32 v[76:77], v[2:3], v[108:109]
	ds_read_b128 v[32:35], v50 offset:7056
	v_pk_fma_f32 v[76:77], v[4:5], v[110:111], v[76:77]
	v_pk_mul_f32 v[80:81], v[116:117], v[124:125] op_sel_hi:[1,0]
	v_add_f32_e32 v78, v76, v77
	v_pk_mul_f32 v[82:83], v[118:119], v[124:125] op_sel_hi:[1,0]
	v_pk_mul_f32 v[84:85], v[70:71], v[2:3]
	v_add_f32_dpp v78, v78, v78 quad_perm:[1,0,3,2] row_mask:0xf bank_mask:0xf bound_ctrl:1
	v_pk_fma_f32 v[84:85], v[72:73], v[4:5], v[84:85]
	v_pk_fma_f32 v[80:81], v[2:3], v[104:105], v[80:81]
	v_add_f32_dpp v78, v78, v78 quad_perm:[2,3,0,1] row_mask:0xf bank_mask:0xf bound_ctrl:1
	v_add_f32_e32 v88, v84, v85
	v_pk_fma_f32 v[82:83], v[4:5], v[106:107], v[82:83]
	v_add_f32_dpp v78, v78, v78 row_half_mirror row_mask:0xf bank_mask:0xf bound_ctrl:1
	ds_read_b128 v[28:31], v50 offset:6800
	ds_read_b128 v[40:43], v50 offset:7568
	v_add_f32_dpp v78, v78, v78 row_mirror row_mask:0xf bank_mask:0xf bound_ctrl:1
	v_pk_fma_f32 v[2:3], v[112:113], v[78:79], v[80:81] op_sel_hi:[1,0,1]
	v_pk_fma_f32 v[4:5], v[114:115], v[78:79], v[82:83] op_sel_hi:[1,0,1]
	ds_read_b32 v48, v51 offset:8080
	ds_read_b128 v[36:39], v50 offset:7312
	ds_read_b128 v[44:47], v50 offset:7824
	s_waitcnt lgkmcnt(6)
; #define LAS __attribute__((address_space(3)))
; __device__ __forceinline__ float allred16(float x) { x += dpp_f<0xB1>(x); x += dpp_f<0x4E>(x); x += dpp_f<0x141>(x); x += dpp_f<0x140>(x); return x; }
; __device__ __forceinline__ void phase_scan(const Args& a, int l, LAS unsigned char* lds) {
;     ...
;                     for (int t = 0; t < TC; ++t) {
;                         f32x4 nw = w, nkk = kk, nbv = bv, nkv = kv, nwr = wr; float nvv = vv;
;                         if (t + 1 < TC) { const LAS float* p = tb + (t + 1) * TOKF;
;                             nw = *(const LAS f32x4*)(p + 4 * j); nkk = *(const LAS f32x4*)(p + 64 + 4 * j); nbv = *(const LAS f32x4*)(p + 128 + 4 * j);
;                             nkv = *(const LAS f32x4*)(p + 192 + 4 * j); nwr = *(const LAS f32x4*)(p + 256 + 4 * j); nvv = p[320 + rowl]; }
;                         f32x2 ta = Sl * kk.lo; ta = Sh * kk.hi + ta;
;                         float pa = ta.x + ta.y;
;                         const f32x2 tl = Sl * w.lo + kv.lo * vv, th = Sh * w.hi + kv.hi * vv;
;                         pa = allred16(pa);
;                         Sl = bv.lo * pa + tl;
;                         Sh = bv.hi * pa + th;
;                         f32x2 ty = Sl * wr.lo; ty = Sh * wr.hi + ty;
;                         float y = ty.x + ty.y;
;                         y = allred16(y);
;                         yv = (j == t) ? y : yv;
;                         w = nw; kk = nkk; bv = nbv; kv = nkv; wr = nwr; vv = nvv;
;                     }
	v_pk_mul_f32 v[76:77], v[2:3], v[10:11]
	ds_read_b128 v[58:61], v50 offset:8416
	v_pk_fma_f32 v[76:77], v[4:5], v[12:13], v[76:77]
	v_pk_mul_f32 v[80:81], v[18:19], v[26:27] op_sel_hi:[1,0]
	v_add_f32_e32 v78, v76, v77
	v_pk_mul_f32 v[82:83], v[20:21], v[26:27] op_sel_hi:[1,0]
	v_pk_mul_f32 v[84:85], v[120:121], v[2:3]
	v_add_f32_dpp v78, v78, v78 quad_perm:[1,0,3,2] row_mask:0xf bank_mask:0xf bound_ctrl:1
	v_pk_fma_f32 v[84:85], v[122:123], v[4:5], v[84:85]
	v_pk_fma_f32 v[80:81], v[2:3], v[6:7], v[80:81]
	v_add_f32_dpp v78, v78, v78 quad_perm:[2,3,0,1] row_mask:0xf bank_mask:0xf bound_ctrl:1
	v_add_f32_e32 v89, v84, v85
	v_pk_fma_f32 v[82:83], v[4:5], v[8:9], v[82:83]
	v_add_f32_dpp v78, v78, v78 row_half_mirror row_mask:0xf bank_mask:0xf bound_ctrl:1
	ds_read_b128 v[54:57], v50 offset:8160
	ds_read_b128 v[66:69], v50 offset:8928
	v_add_f32_dpp v78, v78, v78 row_mirror row_mask:0xf bank_mask:0xf bound_ctrl:1
	v_pk_fma_f32 v[2:3], v[14:15], v[78:79], v[80:81] op_sel_hi:[1,0,1]
	v_pk_fma_f32 v[4:5], v[16:17], v[78:79], v[82:83] op_sel_hi:[1,0,1]
	ds_read_b32 v74, v51 offset:9440
	ds_read_b128 v[62:65], v50 offset:8672
	ds_read_b128 v[70:73], v50 offset:9184
	s_waitcnt lgkmcnt(6)
	v_pk_mul_f32 v[76:77], v[2:3], v[32:33]
	ds_read_b128 v[108:111], v50 offset:9776
	v_pk_fma_f32 v[76:77], v[4:5], v[34:35], v[76:77]
	v_pk_mul_f32 v[80:81], v[40:41], v[48:49] op_sel_hi:[1,0]
	v_add_f32_e32 v78, v76, v77
	v_pk_mul_f32 v[82:83], v[42:43], v[48:49] op_sel_hi:[1,0]
	v_pk_mul_f32 v[84:85], v[22:23], v[2:3]
	v_add_f32_dpp v78, v78, v78 quad_perm:[1,0,3,2] row_mask:0xf bank_mask:0xf bound_ctrl:1
	v_pk_fma_f32 v[84:85], v[24:25], v[4:5], v[84:85]
	v_pk_fma_f32 v[80:81], v[2:3], v[28:29], v[80:81]
	v_add_f32_dpp v78, v78, v78 quad_perm:[2,3,0,1] row_mask:0xf bank_mask:0xf bound_ctrl:1
	v_add_f32_e32 v90, v84, v85
	v_pk_fma_f32 v[82:83], v[4:5], v[30:31], v[82:83]
	v_add_f32_dpp v78, v78, v78 row_half_mirror row_mask:0xf bank_mask:0xf bound_ctrl:1
	ds_read_b128 v[104:107], v50 offset:9520
	ds_read_b128 v[116:119], v50 offset:10288
	v_add_f32_dpp v78, v78, v78 row_mirror row_mask:0xf bank_mask:0xf bound_ctrl:1
	v_pk_fma_f32 v[2:3], v[36:37], v[78:79], v[80:81] op_sel_hi:[1,0,1]
	v_pk_fma_f32 v[4:5], v[38:39], v[78:79], v[82:83] op_sel_hi:[1,0,1]
	ds_read_b32 v124, v51 offset:10800
	ds_read_b128 v[112:115], v50 offset:10032
	ds_read_b128 v[120:123], v50 offset:10544
	s_waitcnt lgkmcnt(6)
	v_pk_mul_f32 v[76:77], v[2:3], v[58:59]
	ds_read_b128 v[10:13], v50 offset:11136
	v_pk_fma_f32 v[76:77], v[4:5], v[60:61], v[76:77]
	v_pk_mul_f32 v[80:81], v[66:67], v[74:75] op_sel_hi:[1,0]
	v_add_f32_e32 v78, v76, v77
	v_pk_mul_f32 v[82:83], v[68:69], v[74:75] op_sel_hi:[1,0]
	v_pk_mul_f32 v[84:85], v[44:45], v[2:3]
	v_add_f32_dpp v78, v78, v78 quad_perm:[1,0,3,2] row_mask:0xf bank_mask:0xf bound_ctrl:1
	v_pk_fma_f32 v[84:85], v[46:47], v[4:5], v[84:85]
	v_pk_fma_f32 v[80:81], v[2:3], v[54:55], v[80:81]
	v_add_f32_dpp v78, v78, v78 quad_perm:[2,3,0,1] row_mask:0xf bank_mask:0xf bound_ctrl:1
	v_add_f32_e32 v91, v84, v85
	v_pk_fma_f32 v[82:83], v[4:5], v[56:57], v[82:83]
	v_add_f32_dpp v78, v78, v78 row_half_mirror row_mask:0xf bank_mask:0xf bound_ctrl:1
	ds_read_b128 v[6:9], v50 offset:10880
	ds_read_b128 v[18:21], v50 offset:11648
	v_add_f32_dpp v78, v78, v78 row_mirror row_mask:0xf bank_mask:0xf bound_ctrl:1
	v_pk_fma_f32 v[2:3], v[62:63], v[78:79], v[80:81] op_sel_hi:[1,0,1]
	v_pk_fma_f32 v[4:5], v[64:65], v[78:79], v[82:83] op_sel_hi:[1,0,1]
	ds_read_b32 v26, v51 offset:12160
	ds_read_b128 v[14:17], v50 offset:11392
	ds_read_b128 v[22:25], v50 offset:11904
	s_waitcnt lgkmcnt(6)
	v_pk_mul_f32 v[76:77], v[2:3], v[108:109]
	ds_read_b128 v[32:35], v50 offset:12496
	v_pk_fma_f32 v[76:77], v[4:5], v[110:111], v[76:77]
	v_pk_mul_f32 v[80:81], v[116:117], v[124:125] op_sel_hi:[1,0]
	v_add_f32_e32 v78, v76, v77
	v_pk_mul_f32 v[82:83], v[118:119], v[124:125] op_sel_hi:[1,0]
	v_pk_mul_f32 v[84:85], v[70:71], v[2:3]
	v_add_f32_dpp v78, v78, v78 quad_perm:[1,0,3,2] row_mask:0xf bank_mask:0xf bound_ctrl:1
	v_pk_fma_f32 v[84:85], v[72:73], v[4:5], v[84:85]
	v_pk_fma_f32 v[80:81], v[2:3], v[104:105], v[80:81]
	v_add_f32_dpp v78, v78, v78 quad_perm:[2,3,0,1] row_mask:0xf bank_mask:0xf bound_ctrl:1
	v_add_f32_e32 v92, v84, v85
	v_pk_fma_f32 v[82:83], v[4:5], v[106:107], v[82:83]
	v_add_f32_dpp v78, v78, v78 row_half_mirror row_mask:0xf bank_mask:0xf bound_ctrl:1
	ds_read_b128 v[28:31], v50 offset:12240
	ds_read_b128 v[40:43], v50 offset:13008
	v_add_f32_dpp v78, v78, v78 row_mirror row_mask:0xf bank_mask:0xf bound_ctrl:1
	v_pk_fma_f32 v[2:3], v[112:113], v[78:79], v[80:81] op_sel_hi:[1,0,1]
	v_pk_fma_f32 v[4:5], v[114:115], v[78:79], v[82:83] op_sel_hi:[1,0,1]
	ds_read_b32 v48, v51 offset:13520
	ds_read_b128 v[36:39], v50 offset:12752
	ds_read_b128 v[44:47], v50 offset:13264
	s_waitcnt lgkmcnt(6)
	v_pk_mul_f32 v[76:77], v[2:3], v[10:11]
	ds_read_b128 v[58:61], v50 offset:13856
	v_pk_fma_f32 v[76:77], v[4:5], v[12:13], v[76:77]
	v_pk_mul_f32 v[80:81], v[18:19], v[26:27] op_sel_hi:[1,0]
	v_add_f32_e32 v78, v76, v77
	v_pk_mul_f32 v[82:83], v[20:21], v[26:27] op_sel_hi:[1,0]
	v_pk_mul_f32 v[84:85], v[120:121], v[2:3]
	v_add_f32_dpp v78, v78, v78 quad_perm:[1,0,3,2] row_mask:0xf bank_mask:0xf bound_ctrl:1
	v_pk_fma_f32 v[84:85], v[122:123], v[4:5], v[84:85]
	v_pk_fma_f32 v[80:81], v[2:3], v[6:7], v[80:81]
	v_add_f32_dpp v78, v78, v78 quad_perm:[2,3,0,1] row_mask:0xf bank_mask:0xf bound_ctrl:1
	v_add_f32_e32 v93, v84, v85
	v_pk_fma_f32 v[82:83], v[4:5], v[8:9], v[82:83]
	v_add_f32_dpp v78, v78, v78 row_half_mirror row_mask:0xf bank_mask:0xf bound_ctrl:1
	ds_read_b128 v[54:57], v50 offset:13600
	ds_read_b128 v[66:69], v50 offset:14368
	v_add_f32_dpp v78, v78, v78 row_mirror row_mask:0xf bank_mask:0xf bound_ctrl:1
	v_pk_fma_f32 v[2:3], v[14:15], v[78:79], v[80:81] op_sel_hi:[1,0,1]
	v_pk_fma_f32 v[4:5], v[16:17], v[78:79], v[82:83] op_sel_hi:[1,0,1]
	ds_read_b32 v74, v51 offset:14880
	ds_read_b128 v[62:65], v50 offset:14112
	ds_read_b128 v[70:73], v50 offset:14624
	s_waitcnt lgkmcnt(6)
; #define LAS __attribute__((address_space(3)))
; __device__ __forceinline__ float allred16(float x) { x += dpp_f<0xB1>(x); x += dpp_f<0x4E>(x); x += dpp_f<0x141>(x); x += dpp_f<0x140>(x); return x; }
; __device__ __forceinline__ void phase_scan(const Args& a, int l, LAS unsigned char* lds) {
;     ...
;                     for (int t = 0; t < TC; ++t) {
;                         f32x4 nw = w, nkk = kk, nbv = bv, nkv = kv, nwr = wr; float nvv = vv;
;                         if (t + 1 < TC) { const LAS float* p = tb + (t + 1) * TOKF;
;                             nw = *(const LAS f32x4*)(p + 4 * j); nkk = *(const LAS f32x4*)(p + 64 + 4 * j); nbv = *(const LAS f32x4*)(p + 128 + 4 * j);
;                             nkv = *(const LAS f32x4*)(p + 192 + 4 * j); nwr = *(const LAS f32x4*)(p + 256 + 4 * j); nvv = p[320 + rowl]; }
;                         f32x2 ta = Sl * kk.lo; ta = Sh * kk.hi + ta;
;                         float pa = ta.x + ta.y;
;                         const f32x2 tl = Sl * w.lo + kv.lo * vv, th = Sh * w.hi + kv.hi * vv;
;                         pa = allred16(pa);
;                         Sl = bv.lo * pa + tl;
;                         Sh = bv.hi * pa + th;
;                         f32x2 ty = Sl * wr.lo; ty = Sh * wr.hi + ty;
;                         float y = ty.x + ty.y;
;                         y = allred16(y);
;                         yv = (j == t) ? y : yv;
;                         w = nw; kk = nkk; bv = nbv; kv = nkv; wr = nwr; vv = nvv;
;                     }
	v_pk_mul_f32 v[76:77], v[2:3], v[32:33]
	ds_read_b128 v[108:111], v50 offset:15216
	v_pk_fma_f32 v[76:77], v[4:5], v[34:35], v[76:77]
	v_pk_mul_f32 v[80:81], v[40:41], v[48:49] op_sel_hi:[1,0]
	v_add_f32_e32 v78, v76, v77
	v_pk_mul_f32 v[82:83], v[42:43], v[48:49] op_sel_hi:[1,0]
	v_pk_mul_f32 v[84:85], v[22:23], v[2:3]
	v_add_f32_dpp v78, v78, v78 quad_perm:[1,0,3,2] row_mask:0xf bank_mask:0xf bound_ctrl:1
	v_pk_fma_f32 v[84:85], v[24:25], v[4:5], v[84:85]
	v_pk_fma_f32 v[80:81], v[2:3], v[28:29], v[80:81]
	v_add_f32_dpp v78, v78, v78 quad_perm:[2,3,0,1] row_mask:0xf bank_mask:0xf bound_ctrl:1
	v_add_f32_e32 v94, v84, v85
	v_pk_fma_f32 v[82:83], v[4:5], v[30:31], v[82:83]
	v_add_f32_dpp v78, v78, v78 row_half_mirror row_mask:0xf bank_mask:0xf bound_ctrl:1
	ds_read_b128 v[104:107], v50 offset:14960
	ds_read_b128 v[116:119], v50 offset:15728
	v_add_f32_dpp v78, v78, v78 row_mirror row_mask:0xf bank_mask:0xf bound_ctrl:1
	v_pk_fma_f32 v[2:3], v[36:37], v[78:79], v[80:81] op_sel_hi:[1,0,1]
	v_pk_fma_f32 v[4:5], v[38:39], v[78:79], v[82:83] op_sel_hi:[1,0,1]
	ds_read_b32 v124, v51 offset:16240
	ds_read_b128 v[112:115], v50 offset:15472
	ds_read_b128 v[120:123], v50 offset:15984
	s_waitcnt lgkmcnt(6)
	v_pk_mul_f32 v[76:77], v[2:3], v[58:59]
	ds_read_b128 v[10:13], v50 offset:16576
	v_pk_fma_f32 v[76:77], v[4:5], v[60:61], v[76:77]
	v_pk_mul_f32 v[80:81], v[66:67], v[74:75] op_sel_hi:[1,0]
	v_add_f32_e32 v78, v76, v77
	v_pk_mul_f32 v[82:83], v[68:69], v[74:75] op_sel_hi:[1,0]
	v_pk_mul_f32 v[84:85], v[44:45], v[2:3]
	v_add_f32_dpp v78, v78, v78 quad_perm:[1,0,3,2] row_mask:0xf bank_mask:0xf bound_ctrl:1
	v_pk_fma_f32 v[84:85], v[46:47], v[4:5], v[84:85]
	v_pk_fma_f32 v[80:81], v[2:3], v[54:55], v[80:81]
	v_add_f32_dpp v78, v78, v78 quad_perm:[2,3,0,1] row_mask:0xf bank_mask:0xf bound_ctrl:1
	v_add_f32_e32 v95, v84, v85
	v_pk_fma_f32 v[82:83], v[4:5], v[56:57], v[82:83]
	v_add_f32_dpp v78, v78, v78 row_half_mirror row_mask:0xf bank_mask:0xf bound_ctrl:1
	ds_read_b128 v[6:9], v50 offset:16320
	ds_read_b128 v[18:21], v50 offset:17088
	v_add_f32_dpp v78, v78, v78 row_mirror row_mask:0xf bank_mask:0xf bound_ctrl:1
	v_pk_fma_f32 v[2:3], v[62:63], v[78:79], v[80:81] op_sel_hi:[1,0,1]
	v_pk_fma_f32 v[4:5], v[64:65], v[78:79], v[82:83] op_sel_hi:[1,0,1]
	ds_read_b32 v26, v51 offset:17600
	ds_read_b128 v[14:17], v50 offset:16832
	ds_read_b128 v[22:25], v50 offset:17344
	s_waitcnt lgkmcnt(6)
	v_pk_mul_f32 v[76:77], v[2:3], v[108:109]
	ds_read_b128 v[32:35], v50 offset:17936
	v_pk_fma_f32 v[76:77], v[4:5], v[110:111], v[76:77]
	v_pk_mul_f32 v[80:81], v[116:117], v[124:125] op_sel_hi:[1,0]
	v_add_f32_e32 v78, v76, v77
	v_pk_mul_f32 v[82:83], v[118:119], v[124:125] op_sel_hi:[1,0]
	v_pk_mul_f32 v[84:85], v[70:71], v[2:3]
	v_add_f32_dpp v78, v78, v78 quad_perm:[1,0,3,2] row_mask:0xf bank_mask:0xf bound_ctrl:1
	v_pk_fma_f32 v[84:85], v[72:73], v[4:5], v[84:85]
	v_pk_fma_f32 v[80:81], v[2:3], v[104:105], v[80:81]
	v_add_f32_dpp v78, v78, v78 quad_perm:[2,3,0,1] row_mask:0xf bank_mask:0xf bound_ctrl:1
	v_add_f32_e32 v126, v84, v85
	v_pk_fma_f32 v[82:83], v[4:5], v[106:107], v[82:83]
	v_add_f32_dpp v78, v78, v78 row_half_mirror row_mask:0xf bank_mask:0xf bound_ctrl:1
	ds_read_b128 v[28:31], v50 offset:17680
	ds_read_b128 v[40:43], v50 offset:18448
	v_add_f32_dpp v78, v78, v78 row_mirror row_mask:0xf bank_mask:0xf bound_ctrl:1
	v_pk_fma_f32 v[2:3], v[112:113], v[78:79], v[80:81] op_sel_hi:[1,0,1]
	v_pk_fma_f32 v[4:5], v[114:115], v[78:79], v[82:83] op_sel_hi:[1,0,1]
	ds_read_b32 v48, v51 offset:18960
	ds_read_b128 v[36:39], v50 offset:18192
	ds_read_b128 v[44:47], v50 offset:18704
	s_waitcnt lgkmcnt(6)
	v_pk_mul_f32 v[76:77], v[2:3], v[10:11]
	ds_read_b128 v[58:61], v50 offset:19296
	v_pk_fma_f32 v[76:77], v[4:5], v[12:13], v[76:77]
	v_pk_mul_f32 v[80:81], v[18:19], v[26:27] op_sel_hi:[1,0]
	v_add_f32_e32 v78, v76, v77
	v_pk_mul_f32 v[82:83], v[20:21], v[26:27] op_sel_hi:[1,0]
	v_pk_mul_f32 v[84:85], v[120:121], v[2:3]
	v_add_f32_dpp v78, v78, v78 quad_perm:[1,0,3,2] row_mask:0xf bank_mask:0xf bound_ctrl:1
	v_pk_fma_f32 v[84:85], v[122:123], v[4:5], v[84:85]
	v_pk_fma_f32 v[80:81], v[2:3], v[6:7], v[80:81]
	v_add_f32_dpp v78, v78, v78 quad_perm:[2,3,0,1] row_mask:0xf bank_mask:0xf bound_ctrl:1
	v_add_f32_e32 v127, v84, v85
	v_pk_fma_f32 v[82:83], v[4:5], v[8:9], v[82:83]
	v_add_f32_dpp v78, v78, v78 row_half_mirror row_mask:0xf bank_mask:0xf bound_ctrl:1
	ds_read_b128 v[54:57], v50 offset:19040
	ds_read_b128 v[66:69], v50 offset:19808
	v_add_f32_dpp v78, v78, v78 row_mirror row_mask:0xf bank_mask:0xf bound_ctrl:1
	v_pk_fma_f32 v[2:3], v[14:15], v[78:79], v[80:81] op_sel_hi:[1,0,1]
	v_pk_fma_f32 v[4:5], v[16:17], v[78:79], v[82:83] op_sel_hi:[1,0,1]
	ds_read_b32 v74, v51 offset:20320
	ds_read_b128 v[62:65], v50 offset:19552
	ds_read_b128 v[70:73], v50 offset:20064
	s_waitcnt lgkmcnt(6)
	v_pk_mul_f32 v[76:77], v[2:3], v[32:33]
	ds_read_b128 v[108:111], v50 offset:20656
	v_pk_fma_f32 v[76:77], v[4:5], v[34:35], v[76:77]
	v_pk_mul_f32 v[80:81], v[40:41], v[48:49] op_sel_hi:[1,0]
	v_add_f32_e32 v78, v76, v77
	v_pk_mul_f32 v[82:83], v[42:43], v[48:49] op_sel_hi:[1,0]
	v_pk_mul_f32 v[84:85], v[22:23], v[2:3]
	v_add_f32_dpp v78, v78, v78 quad_perm:[1,0,3,2] row_mask:0xf bank_mask:0xf bound_ctrl:1
	v_pk_fma_f32 v[84:85], v[24:25], v[4:5], v[84:85]
	v_pk_fma_f32 v[80:81], v[2:3], v[28:29], v[80:81]
	v_add_f32_dpp v78, v78, v78 quad_perm:[2,3,0,1] row_mask:0xf bank_mask:0xf bound_ctrl:1
	v_add_f32_e32 v128, v84, v85
	v_pk_fma_f32 v[82:83], v[4:5], v[30:31], v[82:83]
	v_add_f32_dpp v78, v78, v78 row_half_mirror row_mask:0xf bank_mask:0xf bound_ctrl:1
	ds_read_b128 v[104:107], v50 offset:20400
	ds_read_b128 v[116:119], v50 offset:21168
	v_add_f32_dpp v78, v78, v78 row_mirror row_mask:0xf bank_mask:0xf bound_ctrl:1
	v_pk_fma_f32 v[2:3], v[36:37], v[78:79], v[80:81] op_sel_hi:[1,0,1]
	v_pk_fma_f32 v[4:5], v[38:39], v[78:79], v[82:83] op_sel_hi:[1,0,1]
	ds_read_b32 v124, v51 offset:21680
	ds_read_b128 v[112:115], v50 offset:20912
	ds_read_b128 v[120:123], v50 offset:21424
	s_waitcnt lgkmcnt(6)
; #define LAS __attribute__((address_space(3)))
; __device__ __forceinline__ float allred16(float x) { x += dpp_f<0xB1>(x); x += dpp_f<0x4E>(x); x += dpp_f<0x141>(x); x += dpp_f<0x140>(x); return x; }
; #define SCAN_BAR() do { asm volatile("s_waitcnt lgkmcnt(0)" ::: "memory"); __builtin_amdgcn_s_barrier(); asm volatile("" ::: "memory"); } while (0)
; __device__ __forceinline__ void phase_scan(const Args& a, int l, LAS unsigned char* lds) {
;     ...
;                     for (int t = 0; t < TC; ++t) {
;                         f32x4 nw = w, nkk = kk, nbv = bv, nkv = kv, nwr = wr; float nvv = vv;
;                         if (t + 1 < TC) { const LAS float* p = tb + (t + 1) * TOKF;
;                             nw = *(const LAS f32x4*)(p + 4 * j); nkk = *(const LAS f32x4*)(p + 64 + 4 * j); nbv = *(const LAS f32x4*)(p + 128 + 4 * j);
;                             nkv = *(const LAS f32x4*)(p + 192 + 4 * j); nwr = *(const LAS f32x4*)(p + 256 + 4 * j); nvv = p[320 + rowl]; }
;                         f32x2 ta = Sl * kk.lo; ta = Sh * kk.hi + ta;
;                         float pa = ta.x + ta.y;
;                         const f32x2 tl = Sl * w.lo + kv.lo * vv, th = Sh * w.hi + kv.hi * vv;
;                         pa = allred16(pa);
;                         Sl = bv.lo * pa + tl;
;                         Sh = bv.hi * pa + th;
;                         f32x2 ty = Sl * wr.lo; ty = Sh * wr.hi + ty;
;                         float y = ty.x + ty.y;
;                         y = allred16(y);
;                         yv = (j == t) ? y : yv;
;                         w = nw; kk = nkk; bv = nbv; kv = nkv; wr = nwr; vv = nvv;
;                     }
;                     yb[j * 16 + rowl] = yv;
;                 }
;                 SCAN_BAR();
;             }
	v_pk_mul_f32 v[76:77], v[2:3], v[58:59]
	s_add_i32 vcc_lo, s0, 1
	v_pk_fma_f32 v[76:77], v[4:5], v[60:61], v[76:77]
	v_pk_mul_f32 v[80:81], v[66:67], v[74:75] op_sel_hi:[1,0]
	v_add_f32_e32 v78, v76, v77
	v_pk_mul_f32 v[82:83], v[68:69], v[74:75] op_sel_hi:[1,0]
	v_pk_mul_f32 v[84:85], v[44:45], v[2:3]
	v_add_f32_dpp v78, v78, v78 quad_perm:[1,0,3,2] row_mask:0xf bank_mask:0xf bound_ctrl:1
	v_pk_fma_f32 v[84:85], v[46:47], v[4:5], v[84:85]
	v_pk_fma_f32 v[80:81], v[2:3], v[54:55], v[80:81]
	v_add_f32_dpp v78, v78, v78 quad_perm:[2,3,0,1] row_mask:0xf bank_mask:0xf bound_ctrl:1
	v_add_f32_e32 v129, v84, v85
	v_pk_fma_f32 v[82:83], v[4:5], v[56:57], v[82:83]
	v_add_f32_dpp v78, v78, v78 row_half_mirror row_mask:0xf bank_mask:0xf bound_ctrl:1
	s_and_b32 vcc_hi, vcc_lo, 0xff
	s_mulk_i32 vcc_hi, 0xcd
	v_add_f32_dpp v78, v78, v78 row_mirror row_mask:0xf bank_mask:0xf bound_ctrl:1
	v_pk_fma_f32 v[2:3], v[62:63], v[78:79], v[80:81] op_sel_hi:[1,0,1]
	v_pk_fma_f32 v[4:5], v[64:65], v[78:79], v[82:83] op_sel_hi:[1,0,1]
	s_waitcnt lgkmcnt(0)
	v_pk_mul_f32 v[76:77], v[2:3], v[108:109]
	s_lshr_b32 vcc_hi, vcc_hi, 10
	v_pk_fma_f32 v[76:77], v[4:5], v[110:111], v[76:77]
	v_pk_mul_f32 v[80:81], v[116:117], v[124:125] op_sel_hi:[1,0]
	v_add_f32_e32 v78, v76, v77
	v_pk_mul_f32 v[82:83], v[118:119], v[124:125] op_sel_hi:[1,0]
	v_pk_mul_f32 v[84:85], v[70:71], v[2:3]
	v_add_f32_dpp v78, v78, v78 quad_perm:[1,0,3,2] row_mask:0xf bank_mask:0xf bound_ctrl:1
	v_pk_fma_f32 v[84:85], v[72:73], v[4:5], v[84:85]
	v_pk_fma_f32 v[80:81], v[2:3], v[104:105], v[80:81]
	v_add_f32_dpp v78, v78, v78 quad_perm:[2,3,0,1] row_mask:0xf bank_mask:0xf bound_ctrl:1
	v_add_f32_e32 v130, v84, v85
	v_pk_fma_f32 v[82:83], v[4:5], v[106:107], v[82:83]
	v_add_f32_dpp v78, v78, v78 row_half_mirror row_mask:0xf bank_mask:0xf bound_ctrl:1
	s_mul_i32 vcc_hi, vcc_hi, 5
	s_sub_i32 vcc_lo, vcc_lo, vcc_hi
	v_add_f32_dpp v78, v78, v78 row_mirror row_mask:0xf bank_mask:0xf bound_ctrl:1
	v_pk_fma_f32 v[2:3], v[112:113], v[78:79], v[80:81] op_sel_hi:[1,0,1]
	v_pk_fma_f32 v[4:5], v[114:115], v[78:79], v[82:83] op_sel_hi:[1,0,1]
	v_pk_mul_f32 v[84:85], v[120:121], v[2:3]
	v_lshl_add_u32 v52, s38, 2, v193
	v_pk_fma_f32 v[84:85], v[122:123], v[4:5], v[84:85]
	s_and_b32 vcc_lo, vcc_lo, 0xff
	v_add_f32_e32 v131, v84, v85
	s_mulk_i32 vcc_lo, 0x5500
	v_lshl_add_u32 v50, v192, 2, vcc_lo
	v_lshl_add_u32 v51, v103, 2, vcc_lo
	v_add_f32_dpp v86, v86, v86 row_shl:8 row_mask:0xf bank_mask:0x3 bound_ctrl:1
	v_add_f32_dpp v86, v94, v94 row_shr:8 row_mask:0xf bank_mask:0xc bound_ctrl:1
	v_add_f32_dpp v87, v87, v87 row_shl:8 row_mask:0xf bank_mask:0x3 bound_ctrl:1
	v_add_f32_dpp v87, v95, v95 row_shr:8 row_mask:0xf bank_mask:0xc bound_ctrl:1
	v_add_f32_dpp v88, v88, v88 row_shl:8 row_mask:0xf bank_mask:0x3 bound_ctrl:1
	v_add_f32_dpp v88, v126, v126 row_shr:8 row_mask:0xf bank_mask:0xc bound_ctrl:1
	v_add_f32_dpp v89, v89, v89 row_shl:8 row_mask:0xf bank_mask:0x3 bound_ctrl:1
	v_add_f32_dpp v89, v127, v127 row_shr:8 row_mask:0xf bank_mask:0xc bound_ctrl:1
	v_add_f32_dpp v90, v90, v90 row_shl:8 row_mask:0xf bank_mask:0x3 bound_ctrl:1
	v_add_f32_dpp v90, v128, v128 row_shr:8 row_mask:0xf bank_mask:0xc bound_ctrl:1
	v_add_f32_dpp v91, v91, v91 row_shl:8 row_mask:0xf bank_mask:0x3 bound_ctrl:1
	v_add_f32_dpp v91, v129, v129 row_shr:8 row_mask:0xf bank_mask:0xc bound_ctrl:1
	v_add_f32_dpp v92, v92, v92 row_shl:8 row_mask:0xf bank_mask:0x3 bound_ctrl:1
	v_add_f32_dpp v92, v130, v130 row_shr:8 row_mask:0xf bank_mask:0xc bound_ctrl:1
	v_add_f32_dpp v93, v93, v93 row_shl:8 row_mask:0xf bank_mask:0x3 bound_ctrl:1
	v_add_f32_dpp v93, v131, v131 row_shr:8 row_mask:0xf bank_mask:0xc bound_ctrl:1
	v_cmp_ne_u32_e32 vcc, 0, v138
	v_add_f32_dpp v86, v86, v86 row_shl:4 row_mask:0xf bank_mask:0x5 bound_ctrl:1
	v_add_f32_dpp v86, v90, v90 row_shr:4 row_mask:0xf bank_mask:0xa bound_ctrl:1
	v_add_f32_dpp v87, v87, v87 row_shl:4 row_mask:0xf bank_mask:0x5 bound_ctrl:1
	v_add_f32_dpp v87, v91, v91 row_shr:4 row_mask:0xf bank_mask:0xa bound_ctrl:1
	v_add_f32_dpp v88, v88, v88 row_shl:4 row_mask:0xf bank_mask:0x5 bound_ctrl:1
	v_add_f32_dpp v88, v92, v92 row_shr:4 row_mask:0xf bank_mask:0xa bound_ctrl:1
	v_add_f32_dpp v89, v89, v89 row_shl:4 row_mask:0xf bank_mask:0x5 bound_ctrl:1
	v_add_f32_dpp v89, v93, v93 row_shr:4 row_mask:0xf bank_mask:0xa bound_ctrl:1
	v_add_f32_dpp v86, v86, v86 quad_perm:[2,3,0,1] row_mask:0xf bank_mask:0xf bound_ctrl:1
	v_add_f32_dpp v87, v87, v87 quad_perm:[2,3,0,1] row_mask:0xf bank_mask:0xf bound_ctrl:1
	v_add_f32_dpp v88, v88, v88 quad_perm:[2,3,0,1] row_mask:0xf bank_mask:0xf bound_ctrl:1
	v_add_f32_dpp v89, v89, v89 quad_perm:[2,3,0,1] row_mask:0xf bank_mask:0xf bound_ctrl:1
	v_cndmask_b32_e32 v86, v86, v88, vcc
	v_cndmask_b32_e32 v87, v87, v89, vcc
	v_cmp_ne_u32_e32 vcc, 0, v142
	v_add_f32_dpp v86, v86, v86 quad_perm:[1,0,3,2] row_mask:0xf bank_mask:0xf bound_ctrl:1
	v_add_f32_dpp v87, v87, v87 quad_perm:[1,0,3,2] row_mask:0xf bank_mask:0xf bound_ctrl:1
	v_cndmask_b32_e32 v86, v86, v87, vcc
	ds_write_b32 v52, v86
	s_add_i32 s0, s0, 1
	s_addk_i32 s1, 0x100
	s_and_b32 s38, s1, 0x100
	s_cmpk_eq_i32 s0, 0x100
	s_cbranch_scc0 .Lscan_bar
	s_waitcnt lgkmcnt(0)
	s_barrier
